# XCD-group phase-start stagger (4 groups x ~4us) before P2/P8/P10/P13 so the workgroups' epilogue memory bursts do not coincide
# speedup vs baseline: 1.0051x; 1.0051x over previous
.LBB0_289:
	v_readlane_b32 s0, v254, 15
	s_nop 3
	s_lshr_b32 s0, s0, 5
	s_and_b32 s0, s0, 3
	s_cmp_eq_u32 s0, 0
	s_cbranch_scc1 .Lstag_done_0
.Lstag_loop_0:
	s_sleep 127
	s_sub_u32 s0, s0, 1
	s_cmp_lg_u32 s0, 0
	s_cbranch_scc1 .Lstag_loop_0
